# v82 + accumulator zeroing per unit with 64 v_mov_b64 instead of 128 v_mov_b32
# speedup vs baseline: 1.0071x; 1.0071x over previous
.LBB0_172:
	s_ashr_i32 s59, s58, 31
	s_lshl_b64 s[60:61], s[58:59], 20
	s_add_u32 s60, s88, s60
	s_addc_u32 s61, s44, s61
	s_and_b64 s[62:63], s[0:1], exec
	s_cselect_b32 s55, s61, s67
	s_cselect_b32 s59, s60, s66
	s_ashr_i32 s57, s56, 31
	s_lshl_b64 s[62:63], s[56:57], 20
	s_add_u32 s62, s12, s62
	s_addc_u32 s63, s3, s63
	s_and_b64 s[70:71], s[0:1], exec
	s_cselect_b32 s57, s63, s69
	s_cselect_b32 s65, s62, s68
	s_add_u32 s66, s66, 0x80080
	s_addc_u32 s67, s67, 0
	s_add_u32 s73, s68, 0x100
	v_mov_b64_e32 v[0:1], 0
	v_mov_b64_e32 v[2:3], 0
	v_mov_b64_e32 v[4:5], 0
	v_mov_b64_e32 v[6:7], 0
	v_mov_b64_e32 v[8:9], 0
	v_mov_b64_e32 v[10:11], 0
	v_mov_b64_e32 v[12:13], 0
	v_mov_b64_e32 v[14:15], 0
	v_mov_b64_e32 v[16:17], 0
	v_mov_b64_e32 v[18:19], 0
	v_mov_b64_e32 v[20:21], 0
	v_mov_b64_e32 v[22:23], 0
	v_mov_b64_e32 v[24:25], 0
	v_mov_b64_e32 v[26:27], 0
	v_mov_b64_e32 v[28:29], 0
	v_mov_b64_e32 v[30:31], 0
	v_mov_b64_e32 v[32:33], 0
	v_mov_b64_e32 v[34:35], 0
	v_mov_b64_e32 v[36:37], 0
	v_mov_b64_e32 v[38:39], 0
	v_mov_b64_e32 v[40:41], 0
	v_mov_b64_e32 v[42:43], 0
	v_mov_b64_e32 v[44:45], 0
	v_mov_b64_e32 v[46:47], 0
	v_mov_b64_e32 v[48:49], 0
	v_mov_b64_e32 v[50:51], 0
	v_mov_b64_e32 v[52:53], 0
	v_mov_b64_e32 v[54:55], 0
	v_mov_b64_e32 v[56:57], 0
	v_mov_b64_e32 v[58:59], 0
	v_mov_b64_e32 v[60:61], 0
	v_mov_b64_e32 v[62:63], 0
	v_mov_b64_e32 v[64:65], 0
	v_mov_b64_e32 v[66:67], 0
	v_mov_b64_e32 v[68:69], 0
	v_mov_b64_e32 v[70:71], 0
	v_mov_b64_e32 v[72:73], 0
	v_mov_b64_e32 v[74:75], 0
	v_mov_b64_e32 v[76:77], 0
	v_mov_b64_e32 v[78:79], 0
	v_mov_b64_e32 v[80:81], 0
	v_mov_b64_e32 v[82:83], 0
	v_mov_b64_e32 v[84:85], 0
	v_mov_b64_e32 v[86:87], 0
	v_mov_b64_e32 v[88:89], 0
	v_mov_b64_e32 v[90:91], 0
	v_mov_b64_e32 v[92:93], 0
	v_mov_b64_e32 v[94:95], 0
	v_mov_b64_e32 v[96:97], 0
	v_mov_b64_e32 v[98:99], 0
	v_mov_b64_e32 v[100:101], 0
	v_mov_b64_e32 v[102:103], 0
	v_mov_b64_e32 v[104:105], 0
	v_mov_b64_e32 v[106:107], 0
	v_mov_b64_e32 v[108:109], 0
	v_mov_b64_e32 v[110:111], 0
	v_mov_b64_e32 v[112:113], 0
	v_mov_b64_e32 v[114:115], 0
	v_mov_b64_e32 v[116:117], 0
	v_mov_b64_e32 v[118:119], 0
	v_mov_b64_e32 v[120:121], 0
	v_mov_b64_e32 v[122:123], 0
	v_mov_b64_e32 v[124:125], 0
	v_mov_b64_e32 v[126:127], 0
	s_addc_u32 s76, s69, 0
	s_mov_b32 s77, -2
	s_waitcnt vmcnt(0)

.LBB0_257:
	s_add_u32 s60, s36, 0x100
	v_mov_b64_e32 v[0:1], 0
	v_mov_b64_e32 v[2:3], 0
	v_mov_b64_e32 v[4:5], 0
	v_mov_b64_e32 v[6:7], 0
	v_mov_b64_e32 v[8:9], 0
	v_mov_b64_e32 v[10:11], 0
	v_mov_b64_e32 v[12:13], 0
	v_mov_b64_e32 v[14:15], 0
	v_mov_b64_e32 v[16:17], 0
	v_mov_b64_e32 v[18:19], 0
	v_mov_b64_e32 v[20:21], 0
	v_mov_b64_e32 v[22:23], 0
	v_mov_b64_e32 v[24:25], 0
	v_mov_b64_e32 v[26:27], 0
	v_mov_b64_e32 v[28:29], 0
	v_mov_b64_e32 v[30:31], 0
	v_mov_b64_e32 v[32:33], 0
	v_mov_b64_e32 v[34:35], 0
	v_mov_b64_e32 v[36:37], 0
	v_mov_b64_e32 v[38:39], 0
	v_mov_b64_e32 v[40:41], 0
	v_mov_b64_e32 v[42:43], 0
	v_mov_b64_e32 v[44:45], 0
	v_mov_b64_e32 v[46:47], 0
	v_mov_b64_e32 v[48:49], 0
	v_mov_b64_e32 v[50:51], 0
	v_mov_b64_e32 v[52:53], 0
	v_mov_b64_e32 v[54:55], 0
	v_mov_b64_e32 v[56:57], 0
	v_mov_b64_e32 v[58:59], 0
	v_mov_b64_e32 v[60:61], 0
	v_mov_b64_e32 v[62:63], 0
	v_mov_b64_e32 v[64:65], 0
	v_mov_b64_e32 v[66:67], 0
	v_mov_b64_e32 v[68:69], 0
	v_mov_b64_e32 v[70:71], 0
	v_mov_b64_e32 v[72:73], 0
	v_mov_b64_e32 v[74:75], 0
	v_mov_b64_e32 v[76:77], 0
	v_mov_b64_e32 v[78:79], 0
	v_mov_b64_e32 v[80:81], 0
	v_mov_b64_e32 v[82:83], 0
	v_mov_b64_e32 v[84:85], 0
	v_mov_b64_e32 v[86:87], 0
	v_mov_b64_e32 v[88:89], 0
	v_mov_b64_e32 v[90:91], 0
	v_mov_b64_e32 v[92:93], 0
	v_mov_b64_e32 v[94:95], 0
	v_mov_b64_e32 v[96:97], 0
	v_mov_b64_e32 v[98:99], 0
	v_mov_b64_e32 v[100:101], 0
	v_mov_b64_e32 v[102:103], 0
	v_mov_b64_e32 v[104:105], 0
	v_mov_b64_e32 v[106:107], 0
	v_mov_b64_e32 v[108:109], 0
	v_mov_b64_e32 v[110:111], 0
	v_mov_b64_e32 v[112:113], 0
	v_mov_b64_e32 v[114:115], 0
	v_mov_b64_e32 v[116:117], 0
	v_mov_b64_e32 v[118:119], 0
	v_mov_b64_e32 v[120:121], 0
	v_mov_b64_e32 v[122:123], 0
	v_mov_b64_e32 v[124:125], 0
	v_mov_b64_e32 v[126:127], 0
	s_addc_u32 s61, s37, 0
	s_mov_b32 s62, -2

.LBB0_393:
	s_ashr_i32 s21, s20, 31
	s_lshl_b64 s[22:23], s[20:21], 21
	s_add_u32 s22, s88, s22
	s_addc_u32 s23, s44, s23
	s_and_b64 s[26:27], s[0:1], exec
	s_cselect_b32 s21, s23, s39
	s_cselect_b32 s60, s22, s38
	s_ashr_i32 s15, s14, 31
	s_lshl_b64 s[26:27], s[14:15], 21
	s_add_u32 s26, s3, s26
	s_addc_u32 s27, s45, s27
	s_and_b64 s[56:57], s[0:1], exec
	s_cselect_b32 s15, s27, s41
	s_cselect_b32 s61, s26, s40
	s_add_u32 s38, s38, 0x100080
	s_addc_u32 s39, s39, 0
	s_add_u32 s62, s40, 0x100
	v_mov_b64_e32 v[0:1], 0
	v_mov_b64_e32 v[2:3], 0
	v_mov_b64_e32 v[4:5], 0
	v_mov_b64_e32 v[6:7], 0
	v_mov_b64_e32 v[8:9], 0
	v_mov_b64_e32 v[10:11], 0
	v_mov_b64_e32 v[12:13], 0
	v_mov_b64_e32 v[14:15], 0
	v_mov_b64_e32 v[16:17], 0
	v_mov_b64_e32 v[18:19], 0
	v_mov_b64_e32 v[20:21], 0
	v_mov_b64_e32 v[22:23], 0
	v_mov_b64_e32 v[24:25], 0
	v_mov_b64_e32 v[26:27], 0
	v_mov_b64_e32 v[28:29], 0
	v_mov_b64_e32 v[30:31], 0
	v_mov_b64_e32 v[32:33], 0
	v_mov_b64_e32 v[34:35], 0
	v_mov_b64_e32 v[36:37], 0
	v_mov_b64_e32 v[38:39], 0
	v_mov_b64_e32 v[40:41], 0
	v_mov_b64_e32 v[42:43], 0
	v_mov_b64_e32 v[44:45], 0
	v_mov_b64_e32 v[46:47], 0
	v_mov_b64_e32 v[48:49], 0
	v_mov_b64_e32 v[50:51], 0
	v_mov_b64_e32 v[52:53], 0
	v_mov_b64_e32 v[54:55], 0
	v_mov_b64_e32 v[56:57], 0
	v_mov_b64_e32 v[58:59], 0
	v_mov_b64_e32 v[60:61], 0
	v_mov_b64_e32 v[62:63], 0
	v_mov_b64_e32 v[64:65], 0
	v_mov_b64_e32 v[66:67], 0
	v_mov_b64_e32 v[68:69], 0
	v_mov_b64_e32 v[70:71], 0
	v_mov_b64_e32 v[72:73], 0
	v_mov_b64_e32 v[74:75], 0
	v_mov_b64_e32 v[76:77], 0
	v_mov_b64_e32 v[78:79], 0
	v_mov_b64_e32 v[80:81], 0
	v_mov_b64_e32 v[82:83], 0
	v_mov_b64_e32 v[84:85], 0
	v_mov_b64_e32 v[86:87], 0
	v_mov_b64_e32 v[88:89], 0
	v_mov_b64_e32 v[90:91], 0
	v_mov_b64_e32 v[92:93], 0
	v_mov_b64_e32 v[94:95], 0
	v_mov_b64_e32 v[96:97], 0
	v_mov_b64_e32 v[98:99], 0
	v_mov_b64_e32 v[100:101], 0
	v_mov_b64_e32 v[102:103], 0
	v_mov_b64_e32 v[104:105], 0
	v_mov_b64_e32 v[106:107], 0
	v_mov_b64_e32 v[108:109], 0
	v_mov_b64_e32 v[110:111], 0
	v_mov_b64_e32 v[112:113], 0
	v_mov_b64_e32 v[114:115], 0
	v_mov_b64_e32 v[116:117], 0
	v_mov_b64_e32 v[118:119], 0
	v_mov_b64_e32 v[120:121], 0
	v_mov_b64_e32 v[122:123], 0
	v_mov_b64_e32 v[124:125], 0
	v_mov_b64_e32 v[126:127], 0
	s_addc_u32 s63, s41, 0
	s_mov_b32 s64, -2

.LBB0_621:
	s_ashr_i32 s25, s24, 31
	s_lshl_b64 s[26:27], s[24:25], 21
	s_add_u32 s26, s3, s26
	s_addc_u32 s27, s28, s27
	s_and_b64 s[36:37], s[0:1], exec
	s_cselect_b32 s25, s27, s41
	s_cselect_b32 s57, s26, s40
	s_ashr_i32 s23, s22, 31
	s_lshl_b64 s[36:37], s[22:23], 21
	s_add_u32 s36, s78, s36
	s_addc_u32 s37, s81, s37
	s_and_b64 s[44:45], s[0:1], exec
	s_cselect_b32 s23, s37, s43
	s_cselect_b32 s58, s36, s42
	s_add_u32 s40, s40, 0x100080
	s_addc_u32 s41, s41, 0
	s_add_u32 s59, s42, 0x100
	v_mov_b64_e32 v[0:1], 0
	v_mov_b64_e32 v[2:3], 0
	v_mov_b64_e32 v[4:5], 0
	v_mov_b64_e32 v[6:7], 0
	v_mov_b64_e32 v[8:9], 0
	v_mov_b64_e32 v[10:11], 0
	v_mov_b64_e32 v[12:13], 0
	v_mov_b64_e32 v[14:15], 0
	v_mov_b64_e32 v[16:17], 0
	v_mov_b64_e32 v[18:19], 0
	v_mov_b64_e32 v[20:21], 0
	v_mov_b64_e32 v[22:23], 0
	v_mov_b64_e32 v[24:25], 0
	v_mov_b64_e32 v[26:27], 0
	v_mov_b64_e32 v[28:29], 0
	v_mov_b64_e32 v[30:31], 0
	v_mov_b64_e32 v[32:33], 0
	v_mov_b64_e32 v[34:35], 0
	v_mov_b64_e32 v[36:37], 0
	v_mov_b64_e32 v[38:39], 0
	v_mov_b64_e32 v[40:41], 0
	v_mov_b64_e32 v[42:43], 0
	v_mov_b64_e32 v[44:45], 0
	v_mov_b64_e32 v[46:47], 0
	v_mov_b64_e32 v[48:49], 0
	v_mov_b64_e32 v[50:51], 0
	v_mov_b64_e32 v[52:53], 0
	v_mov_b64_e32 v[54:55], 0
	v_mov_b64_e32 v[56:57], 0
	v_mov_b64_e32 v[58:59], 0
	v_mov_b64_e32 v[60:61], 0
	v_mov_b64_e32 v[62:63], 0
	v_mov_b64_e32 v[64:65], 0
	v_mov_b64_e32 v[66:67], 0
	v_mov_b64_e32 v[68:69], 0
	v_mov_b64_e32 v[70:71], 0
	v_mov_b64_e32 v[72:73], 0
	v_mov_b64_e32 v[74:75], 0
	v_mov_b64_e32 v[76:77], 0
	v_mov_b64_e32 v[78:79], 0
	v_mov_b64_e32 v[80:81], 0
	v_mov_b64_e32 v[82:83], 0
	v_mov_b64_e32 v[84:85], 0
	v_mov_b64_e32 v[86:87], 0
	v_mov_b64_e32 v[88:89], 0
	v_mov_b64_e32 v[90:91], 0
	v_mov_b64_e32 v[92:93], 0
	v_mov_b64_e32 v[94:95], 0
	v_mov_b64_e32 v[96:97], 0
	v_mov_b64_e32 v[98:99], 0
	v_mov_b64_e32 v[100:101], 0
	v_mov_b64_e32 v[102:103], 0
	v_mov_b64_e32 v[104:105], 0
	v_mov_b64_e32 v[106:107], 0
	v_mov_b64_e32 v[108:109], 0
	v_mov_b64_e32 v[110:111], 0
	v_mov_b64_e32 v[112:113], 0
	v_mov_b64_e32 v[114:115], 0
	v_mov_b64_e32 v[116:117], 0
	v_mov_b64_e32 v[118:119], 0
	v_mov_b64_e32 v[120:121], 0
	v_mov_b64_e32 v[122:123], 0
	v_mov_b64_e32 v[124:125], 0
	v_mov_b64_e32 v[126:127], 0
	s_addc_u32 s60, s43, 0
	s_mov_b32 s61, -2

.LBB0_772:
	s_ashr_i32 s23, s22, 31
	s_lshl_b64 s[24:25], s[22:23], 20
	s_add_u32 s24, s88, s24
	s_addc_u32 s25, s39, s25
	s_and_b64 s[26:27], s[0:1], exec
	s_cselect_b32 s23, s25, s31
	s_cselect_b32 s48, s24, s30
	s_ashr_i32 s21, s20, 31
	s_lshl_b64 s[26:27], s[20:21], 20
	s_add_u32 s26, s8, s26
	s_addc_u32 s27, s64, s27
	s_and_b64 s[38:39], s[0:1], exec
	s_cselect_b32 s21, s27, s37
	s_cselect_b32 s49, s26, s36
	s_add_u32 s30, s30, 0x80080
	s_addc_u32 s31, s31, 0
	s_add_u32 s50, s36, 0x100
	v_mov_b64_e32 v[0:1], 0
	v_mov_b64_e32 v[2:3], 0
	v_mov_b64_e32 v[4:5], 0
	v_mov_b64_e32 v[6:7], 0
	v_mov_b64_e32 v[8:9], 0
	v_mov_b64_e32 v[10:11], 0
	v_mov_b64_e32 v[12:13], 0
	v_mov_b64_e32 v[14:15], 0
	v_mov_b64_e32 v[16:17], 0
	v_mov_b64_e32 v[18:19], 0
	v_mov_b64_e32 v[20:21], 0
	v_mov_b64_e32 v[22:23], 0
	v_mov_b64_e32 v[24:25], 0
	v_mov_b64_e32 v[26:27], 0
	v_mov_b64_e32 v[28:29], 0
	v_mov_b64_e32 v[30:31], 0
	v_mov_b64_e32 v[32:33], 0
	v_mov_b64_e32 v[34:35], 0
	v_mov_b64_e32 v[36:37], 0
	v_mov_b64_e32 v[38:39], 0
	v_mov_b64_e32 v[40:41], 0
	v_mov_b64_e32 v[42:43], 0
	v_mov_b64_e32 v[44:45], 0
	v_mov_b64_e32 v[46:47], 0
	v_mov_b64_e32 v[48:49], 0
	v_mov_b64_e32 v[50:51], 0
	v_mov_b64_e32 v[52:53], 0
	v_mov_b64_e32 v[54:55], 0
	v_mov_b64_e32 v[56:57], 0
	v_mov_b64_e32 v[58:59], 0
	v_mov_b64_e32 v[60:61], 0
	v_mov_b64_e32 v[62:63], 0
	v_mov_b64_e32 v[64:65], 0
	v_mov_b64_e32 v[66:67], 0
	v_mov_b64_e32 v[68:69], 0
	v_mov_b64_e32 v[70:71], 0
	v_mov_b64_e32 v[72:73], 0
	v_mov_b64_e32 v[74:75], 0
	v_mov_b64_e32 v[76:77], 0
	v_mov_b64_e32 v[78:79], 0
	v_mov_b64_e32 v[80:81], 0
	v_mov_b64_e32 v[82:83], 0
	v_mov_b64_e32 v[84:85], 0
	v_mov_b64_e32 v[86:87], 0
	v_mov_b64_e32 v[88:89], 0
	v_mov_b64_e32 v[90:91], 0
	v_mov_b64_e32 v[92:93], 0
	v_mov_b64_e32 v[94:95], 0
	v_mov_b64_e32 v[96:97], 0
	v_mov_b64_e32 v[98:99], 0
	v_mov_b64_e32 v[100:101], 0
	v_mov_b64_e32 v[102:103], 0
	v_mov_b64_e32 v[104:105], 0
	v_mov_b64_e32 v[106:107], 0
	v_mov_b64_e32 v[108:109], 0
	v_mov_b64_e32 v[110:111], 0
	v_mov_b64_e32 v[112:113], 0
	v_mov_b64_e32 v[114:115], 0
	v_mov_b64_e32 v[116:117], 0
	v_mov_b64_e32 v[118:119], 0
	v_mov_b64_e32 v[120:121], 0
	v_mov_b64_e32 v[122:123], 0
	v_mov_b64_e32 v[124:125], 0
	v_mov_b64_e32 v[126:127], 0
	s_addc_u32 s51, s37, 0
	s_mov_b32 s52, -2

.LBB0_857:
	s_add_u32 s52, s26, 0x100
	v_mov_b64_e32 v[0:1], 0
	v_mov_b64_e32 v[2:3], 0
	v_mov_b64_e32 v[4:5], 0
	v_mov_b64_e32 v[6:7], 0
	v_mov_b64_e32 v[8:9], 0
	v_mov_b64_e32 v[10:11], 0
	v_mov_b64_e32 v[12:13], 0
	v_mov_b64_e32 v[14:15], 0
	v_mov_b64_e32 v[16:17], 0
	v_mov_b64_e32 v[18:19], 0
	v_mov_b64_e32 v[20:21], 0
	v_mov_b64_e32 v[22:23], 0
	v_mov_b64_e32 v[24:25], 0
	v_mov_b64_e32 v[26:27], 0
	v_mov_b64_e32 v[28:29], 0
	v_mov_b64_e32 v[30:31], 0
	v_mov_b64_e32 v[32:33], 0
	v_mov_b64_e32 v[34:35], 0
	v_mov_b64_e32 v[36:37], 0
	v_mov_b64_e32 v[38:39], 0
	v_mov_b64_e32 v[40:41], 0
	v_mov_b64_e32 v[42:43], 0
	v_mov_b64_e32 v[44:45], 0
	v_mov_b64_e32 v[46:47], 0
	v_mov_b64_e32 v[48:49], 0
	v_mov_b64_e32 v[50:51], 0
	v_mov_b64_e32 v[52:53], 0
	v_mov_b64_e32 v[54:55], 0
	v_mov_b64_e32 v[56:57], 0
	v_mov_b64_e32 v[58:59], 0
	v_mov_b64_e32 v[60:61], 0
	v_mov_b64_e32 v[62:63], 0
	v_mov_b64_e32 v[64:65], 0
	v_mov_b64_e32 v[66:67], 0
	v_mov_b64_e32 v[68:69], 0
	v_mov_b64_e32 v[70:71], 0
	v_mov_b64_e32 v[72:73], 0
	v_mov_b64_e32 v[74:75], 0
	v_mov_b64_e32 v[76:77], 0
	v_mov_b64_e32 v[78:79], 0
	v_mov_b64_e32 v[80:81], 0
	v_mov_b64_e32 v[82:83], 0
	v_mov_b64_e32 v[84:85], 0
	v_mov_b64_e32 v[86:87], 0
	v_mov_b64_e32 v[88:89], 0
	v_mov_b64_e32 v[90:91], 0
	v_mov_b64_e32 v[92:93], 0
	v_mov_b64_e32 v[94:95], 0
	v_mov_b64_e32 v[96:97], 0
	v_mov_b64_e32 v[98:99], 0
	v_mov_b64_e32 v[100:101], 0
	v_mov_b64_e32 v[102:103], 0
	v_mov_b64_e32 v[104:105], 0
	v_mov_b64_e32 v[106:107], 0
	v_mov_b64_e32 v[108:109], 0
	v_mov_b64_e32 v[110:111], 0
	v_mov_b64_e32 v[112:113], 0
	v_mov_b64_e32 v[114:115], 0
	v_mov_b64_e32 v[116:117], 0
	v_mov_b64_e32 v[118:119], 0
	v_mov_b64_e32 v[120:121], 0
	v_mov_b64_e32 v[122:123], 0
	v_mov_b64_e32 v[124:125], 0
	v_mov_b64_e32 v[126:127], 0
	s_addc_u32 s53, s27, 0
	s_mov_b32 s54, -2
